# GEMM1 exit: leave the last tile's 16 epilogue stores in flight (vmcnt(16)) when entering side_gemm1
# baseline (speedup 1.0000x reference)
; #define PG8_WAIT_V(n) asm volatile("s_waitcnt vmcnt(" #n ")" ::: "memory")
; #define PG8_BAR __builtin_amdgcn_s_barrier()
; template <class Epi, class Sched, bool ALIGN_EPI = false, bool SP2 = false>
; __device__ __forceinline__ void gemm_phase(PG8_LAS unsigned char* lds, const Gemm g, const Sched& S, const Epi& E) {
;     ...
;     PG8_WAIT_V(0);
;     if constexpr (!ALIGN_EPI) { if (wr == 0) PG8_BAR; }
;     PG8_BAR;
.LBB0_92:
	s_waitcnt vmcnt(16)
	v_readlane_b32 s34, v254, 50
	v_readlane_b32 s36, v252, 8
	v_readlane_b32 s35, v254, 51
	s_barrier
	v_readlane_b32 s37, v252, 9
	v_readlane_b32 s38, v252, 10
	v_readlane_b32 s39, v252, 11
	v_readlane_b32 s40, v252, 12
	v_readlane_b32 s41, v252, 13
	v_readlane_b32 s42, v252, 14
	v_readlane_b32 s43, v252, 15
	v_readlane_b32 s44, v252, 16
	v_readlane_b32 s45, v252, 17
	v_readlane_b32 s46, v252, 18
	v_readlane_b32 s47, v252, 19
	v_readlane_b32 s48, v252, 20
	v_readlane_b32 s49, v252, 21
	v_readlane_b32 s50, v252, 22
	v_readlane_b32 s51, v252, 23
